# merge epilogue hand-written: all gate/merged loads issued up front, counted vmcnt, separate z=0 / z!=0 straight-line variants
# speedup vs baseline: 1.0024x; 1.0024x over previous
.LBB0_1020:
	s_lshl_b32 s13, s20, 8
	s_lshl_b32 s20, s5, 10
	v_mbcnt_lo_u32_b32 v16, -1, 0
	v_mbcnt_hi_u32_b32 v16, -1, v16
	s_lshl_b32 s4, s4, 8
	v_and_or_b32 v176, v16, 15, s45
	s_ashr_i32 s21, s20, 31
	v_ashrrev_i32_e32 v16, 1, v16
	v_add_u32_e32 v168, s13, v176
	s_or_b32 s4, s4, s46
	s_lshl_b64 s[20:21], s[20:21], 1
	v_and_b32_e32 v16, -8, v16
	s_add_u32 s20, s43, s20
	v_ashrrev_i32_e32 v169, 31, v168
	v_add_u32_e32 v166, s4, v16
	s_addc_u32 s21, s44, s21
	v_lshlrev_b64 v[16:17], 13, v[168:169]
	v_lshl_add_u64 v[16:17], s[20:21], 0, v[16:17]
	v_ashrrev_i32_e32 v167, 31, v166
	v_lshl_add_u64 v[16:17], v[166:167], 1, v[16:17]
	v_lshlrev_b64 v[18:19], 11, v[168:169]
	v_lshl_add_u64 v[18:19], s[8:9], 0, v[18:19]
	v_lshl_add_u64 v[172:173], v[166:167], 1, v[18:19]
	v_mov_b64_e32 v[170:171], v[16:17]
	v_mov_b64_e32 v[230:231], v[250:251]
	v_mov_b32_e32 v243, v249
	v_mov_b32_e32 v251, v248
	v_mov_b32_e32 v249, 0x358637bd
	v_mov_b32_e32 v248, 0x260
	s_mov_b32 s59, 0
	s_waitcnt lgkmcnt(0)
	s_cmp_eq_u32 s5, 0
	s_cbranch_scc1 .Lmepi_z0
	global_load_dwordx4 v[180:183], v[170:171], off nt
	global_load_dwordx4 v[184:187], v[170:171], off offset:256 nt
	global_load_dwordx4 v[188:191], v[172:173], off
	global_load_dwordx4 v[192:195], v[172:173], off offset:256
	s_mov_b32 s58, 0x20000
	v_lshl_add_u64 v[244:245], v[170:171], 0, s[58:59]
	global_load_dwordx4 v[196:199], v[244:245], off nt
	global_load_dwordx4 v[200:203], v[244:245], off offset:256 nt
	s_mov_b32 s58, 0x8000
	v_lshl_add_u64 v[246:247], v[172:173], 0, s[58:59]
	global_load_dwordx4 v[204:207], v[246:247], off
	global_load_dwordx4 v[208:211], v[246:247], off offset:256
	s_mov_b32 s58, 0x40000
	v_lshl_add_u64 v[252:253], v[170:171], 0, s[58:59]
	global_load_dwordx4 v[222:225], v[252:253], off nt
	global_load_dwordx4 v[226:229], v[252:253], off offset:256 nt
	s_mov_b32 s58, 0x10000
	v_lshl_add_u64 v[178:179], v[172:173], 0, s[58:59]
	global_load_dwordx4 v[234:237], v[178:179], off
	global_load_dwordx4 v[238:241], v[178:179], off offset:256
	s_mov_b32 s58, 0x60000
	v_lshl_add_u64 v[244:245], v[170:171], 0, s[58:59]
	global_load_dwordx4 v[16:19], v[244:245], off nt
	global_load_dwordx4 v[24:27], v[244:245], off offset:256 nt
	s_mov_b32 s58, 0x18000
	v_lshl_add_u64 v[246:247], v[172:173], 0, s[58:59]
	global_load_dwordx4 v[32:35], v[246:247], off
	global_load_dwordx4 v[44:47], v[246:247], off offset:256
	s_mov_b32 s58, 0x100000
	v_lshl_add_u64 v[252:253], v[170:171], 0, s[58:59]
	global_load_dwordx4 v[136:139], v[252:253], off nt
	global_load_dwordx4 v[148:151], v[252:253], off offset:256 nt
	s_mov_b32 s58, 0x40000
	v_lshl_add_u64 v[178:179], v[172:173], 0, s[58:59]
	global_load_dwordx4 v[152:155], v[178:179], off
	global_load_dwordx4 v[156:159], v[178:179], off offset:256
	s_waitcnt vmcnt(17)
	v_lshlrev_b32_e32 v244, 16, v180
	v_and_b32_e32 v245, 0xffff0000, v180
	v_pk_mul_f32 v[144:145], v[144:145], v[244:245]
	v_lshlrev_b32_e32 v246, 16, v181
	v_and_b32_e32 v247, 0xffff0000, v181
	v_pk_mul_f32 v[146:147], v[146:147], v[246:247]
	v_lshlrev_b32_e32 v252, 16, v182
	v_and_b32_e32 v253, 0xffff0000, v182
	v_pk_mul_f32 v[140:141], v[140:141], v[252:253]
	v_lshlrev_b32_e32 v178, 16, v183
	v_and_b32_e32 v179, 0xffff0000, v183
	v_pk_mul_f32 v[142:143], v[142:143], v[178:179]
	v_lshlrev_b32_e32 v244, 16, v188
	v_and_b32_e32 v245, 0xffff0000, v188
	v_pk_add_f32 v[144:145], v[144:145], v[244:245]
	v_lshlrev_b32_e32 v246, 16, v189
	v_and_b32_e32 v247, 0xffff0000, v189
	v_pk_add_f32 v[146:147], v[146:147], v[246:247]
	v_lshlrev_b32_e32 v252, 16, v190
	v_and_b32_e32 v253, 0xffff0000, v190
	v_pk_add_f32 v[140:141], v[140:141], v[252:253]
	v_lshlrev_b32_e32 v178, 16, v191
	v_and_b32_e32 v179, 0xffff0000, v191
	v_pk_add_f32 v[142:143], v[142:143], v[178:179]
	v_cvt_pk_bf16_f32 v180, v144, v145
	v_cvt_pk_bf16_f32 v181, v146, v147
	v_cvt_pk_bf16_f32 v182, v140, v141
	v_cvt_pk_bf16_f32 v183, v142, v143
	global_store_dwordx4 v[172:173], v[180:183], off
	s_waitcnt vmcnt(17)
	v_lshlrev_b32_e32 v244, 16, v184
	v_and_b32_e32 v245, 0xffff0000, v184
	v_pk_mul_f32 v[132:133], v[132:133], v[244:245]
	v_lshlrev_b32_e32 v246, 16, v185
	v_and_b32_e32 v247, 0xffff0000, v185
	v_pk_mul_f32 v[134:135], v[134:135], v[246:247]
	v_lshlrev_b32_e32 v252, 16, v186
	v_and_b32_e32 v253, 0xffff0000, v186
	v_pk_mul_f32 v[128:129], v[128:129], v[252:253]
	v_lshlrev_b32_e32 v178, 16, v187
	v_and_b32_e32 v179, 0xffff0000, v187
	v_pk_mul_f32 v[130:131], v[130:131], v[178:179]
	v_lshlrev_b32_e32 v244, 16, v192
	v_and_b32_e32 v245, 0xffff0000, v192
	v_pk_add_f32 v[132:133], v[132:133], v[244:245]
	v_lshlrev_b32_e32 v246, 16, v193
	v_and_b32_e32 v247, 0xffff0000, v193
	v_pk_add_f32 v[134:135], v[134:135], v[246:247]
	v_lshlrev_b32_e32 v252, 16, v194
	v_and_b32_e32 v253, 0xffff0000, v194
	v_pk_add_f32 v[128:129], v[128:129], v[252:253]
	v_lshlrev_b32_e32 v178, 16, v195
	v_and_b32_e32 v179, 0xffff0000, v195
	v_pk_add_f32 v[130:131], v[130:131], v[178:179]
	v_cvt_pk_bf16_f32 v184, v132, v133
	v_cvt_pk_bf16_f32 v185, v134, v135
	v_cvt_pk_bf16_f32 v186, v128, v129
	v_cvt_pk_bf16_f32 v187, v130, v131
	global_store_dwordx4 v[172:173], v[184:187], off offset:256
	s_mov_b32 s58, 0x120000
	v_lshl_add_u64 v[244:245], v[170:171], 0, s[58:59]
	global_load_dwordx4 v[140:143], v[244:245], off nt
	global_load_dwordx4 v[144:147], v[244:245], off offset:256 nt
	s_mov_b32 s58, 0x48000
	v_lshl_add_u64 v[246:247], v[172:173], 0, s[58:59]
	global_load_dwordx4 v[180:183], v[246:247], off
	global_load_dwordx4 v[188:191], v[246:247], off offset:256
	s_mov_b32 s58, 0x140000
	v_lshl_add_u64 v[252:253], v[170:171], 0, s[58:59]
	global_load_dwordx4 v[128:131], v[252:253], off nt
	global_load_dwordx4 v[132:135], v[252:253], off offset:256 nt
	s_mov_b32 s58, 0x50000
	v_lshl_add_u64 v[178:179], v[172:173], 0, s[58:59]
	global_load_dwordx4 v[184:187], v[178:179], off
	global_load_dwordx4 v[192:195], v[178:179], off offset:256
	s_waitcnt vmcnt(23)
	v_lshlrev_b32_e32 v244, 16, v196
	v_and_b32_e32 v245, 0xffff0000, v196
	v_pk_mul_f32 v[124:125], v[124:125], v[244:245]
	v_lshlrev_b32_e32 v246, 16, v197
	v_and_b32_e32 v247, 0xffff0000, v197
	v_pk_mul_f32 v[126:127], v[126:127], v[246:247]
	v_lshlrev_b32_e32 v252, 16, v198
	v_and_b32_e32 v253, 0xffff0000, v198
	v_pk_mul_f32 v[120:121], v[120:121], v[252:253]
	v_lshlrev_b32_e32 v178, 16, v199
	v_and_b32_e32 v179, 0xffff0000, v199
	v_pk_mul_f32 v[122:123], v[122:123], v[178:179]
	v_lshlrev_b32_e32 v244, 16, v204
	v_and_b32_e32 v245, 0xffff0000, v204
	v_pk_add_f32 v[124:125], v[124:125], v[244:245]
	v_lshlrev_b32_e32 v246, 16, v205
	v_and_b32_e32 v247, 0xffff0000, v205
	v_pk_add_f32 v[126:127], v[126:127], v[246:247]
	v_lshlrev_b32_e32 v252, 16, v206
	v_and_b32_e32 v253, 0xffff0000, v206
	v_pk_add_f32 v[120:121], v[120:121], v[252:253]
	v_lshlrev_b32_e32 v178, 16, v207
	v_and_b32_e32 v179, 0xffff0000, v207
	v_pk_add_f32 v[122:123], v[122:123], v[178:179]
	v_cvt_pk_bf16_f32 v196, v124, v125
	v_cvt_pk_bf16_f32 v197, v126, v127
	v_cvt_pk_bf16_f32 v198, v120, v121
	v_cvt_pk_bf16_f32 v199, v122, v123
	s_mov_b32 s58, 0x8000
	v_lshl_add_u64 v[244:245], v[172:173], 0, s[58:59]
	global_store_dwordx4 v[244:245], v[196:199], off
	s_waitcnt vmcnt(23)
	v_lshlrev_b32_e32 v246, 16, v200
	v_and_b32_e32 v247, 0xffff0000, v200
	v_pk_mul_f32 v[116:117], v[116:117], v[246:247]
	v_lshlrev_b32_e32 v252, 16, v201
	v_and_b32_e32 v253, 0xffff0000, v201
	v_pk_mul_f32 v[118:119], v[118:119], v[252:253]
	v_lshlrev_b32_e32 v178, 16, v202
	v_and_b32_e32 v179, 0xffff0000, v202
	v_pk_mul_f32 v[112:113], v[112:113], v[178:179]
	v_lshlrev_b32_e32 v244, 16, v203
	v_and_b32_e32 v245, 0xffff0000, v203
	v_pk_mul_f32 v[114:115], v[114:115], v[244:245]
	v_lshlrev_b32_e32 v246, 16, v208
	v_and_b32_e32 v247, 0xffff0000, v208
	v_pk_add_f32 v[116:117], v[116:117], v[246:247]
	v_lshlrev_b32_e32 v252, 16, v209
	v_and_b32_e32 v253, 0xffff0000, v209
	v_pk_add_f32 v[118:119], v[118:119], v[252:253]
	v_lshlrev_b32_e32 v178, 16, v210
	v_and_b32_e32 v179, 0xffff0000, v210
	v_pk_add_f32 v[112:113], v[112:113], v[178:179]
	v_lshlrev_b32_e32 v244, 16, v211
	v_and_b32_e32 v245, 0xffff0000, v211
	v_pk_add_f32 v[114:115], v[114:115], v[244:245]
	v_cvt_pk_bf16_f32 v200, v116, v117
	v_cvt_pk_bf16_f32 v201, v118, v119
	v_cvt_pk_bf16_f32 v202, v112, v113
	v_cvt_pk_bf16_f32 v203, v114, v115
	s_mov_b32 s58, 0x8000
	v_lshl_add_u64 v[246:247], v[172:173], 0, s[58:59]
	global_store_dwordx4 v[246:247], v[200:203], off offset:256
	s_mov_b32 s58, 0x160000
	v_lshl_add_u64 v[252:253], v[170:171], 0, s[58:59]
	global_load_dwordx4 v[120:123], v[252:253], off nt
	global_load_dwordx4 v[124:127], v[252:253], off offset:256 nt
	s_mov_b32 s58, 0x58000
	v_lshl_add_u64 v[178:179], v[172:173], 0, s[58:59]
	global_load_dwordx4 v[196:199], v[178:179], off
	global_load_dwordx4 v[204:207], v[178:179], off offset:256
	s_waitcnt vmcnt(25)
	v_lshlrev_b32_e32 v244, 16, v222
	v_and_b32_e32 v245, 0xffff0000, v222
	v_pk_mul_f32 v[108:109], v[108:109], v[244:245]
	v_lshlrev_b32_e32 v246, 16, v223
	v_and_b32_e32 v247, 0xffff0000, v223
	v_pk_mul_f32 v[110:111], v[110:111], v[246:247]
	v_lshlrev_b32_e32 v252, 16, v224
	v_and_b32_e32 v253, 0xffff0000, v224
	v_pk_mul_f32 v[104:105], v[104:105], v[252:253]
	v_lshlrev_b32_e32 v178, 16, v225
	v_and_b32_e32 v179, 0xffff0000, v225
	v_pk_mul_f32 v[106:107], v[106:107], v[178:179]
	v_lshlrev_b32_e32 v244, 16, v234
	v_and_b32_e32 v245, 0xffff0000, v234
	v_pk_add_f32 v[108:109], v[108:109], v[244:245]
	v_lshlrev_b32_e32 v246, 16, v235
	v_and_b32_e32 v247, 0xffff0000, v235
	v_pk_add_f32 v[110:111], v[110:111], v[246:247]
	v_lshlrev_b32_e32 v252, 16, v236
	v_and_b32_e32 v253, 0xffff0000, v236
	v_pk_add_f32 v[104:105], v[104:105], v[252:253]
	v_lshlrev_b32_e32 v178, 16, v237
	v_and_b32_e32 v179, 0xffff0000, v237
	v_pk_add_f32 v[106:107], v[106:107], v[178:179]
	v_cvt_pk_bf16_f32 v222, v108, v109
	v_cvt_pk_bf16_f32 v223, v110, v111
	v_cvt_pk_bf16_f32 v224, v104, v105
	v_cvt_pk_bf16_f32 v225, v106, v107
	s_mov_b32 s58, 0x10000
	v_lshl_add_u64 v[244:245], v[172:173], 0, s[58:59]
	global_store_dwordx4 v[244:245], v[222:225], off
	s_waitcnt vmcnt(25)
	v_lshlrev_b32_e32 v246, 16, v226
	v_and_b32_e32 v247, 0xffff0000, v226
	v_pk_mul_f32 v[100:101], v[100:101], v[246:247]
	v_lshlrev_b32_e32 v252, 16, v227
	v_and_b32_e32 v253, 0xffff0000, v227
	v_pk_mul_f32 v[102:103], v[102:103], v[252:253]
	v_lshlrev_b32_e32 v178, 16, v228
	v_and_b32_e32 v179, 0xffff0000, v228
	v_pk_mul_f32 v[96:97], v[96:97], v[178:179]
	v_lshlrev_b32_e32 v244, 16, v229
	v_and_b32_e32 v245, 0xffff0000, v229
	v_pk_mul_f32 v[98:99], v[98:99], v[244:245]
	v_lshlrev_b32_e32 v246, 16, v238
	v_and_b32_e32 v247, 0xffff0000, v238
	v_pk_add_f32 v[100:101], v[100:101], v[246:247]
	v_lshlrev_b32_e32 v252, 16, v239
	v_and_b32_e32 v253, 0xffff0000, v239
	v_pk_add_f32 v[102:103], v[102:103], v[252:253]
	v_lshlrev_b32_e32 v178, 16, v240
	v_and_b32_e32 v179, 0xffff0000, v240
	v_pk_add_f32 v[96:97], v[96:97], v[178:179]
	v_lshlrev_b32_e32 v244, 16, v241
	v_and_b32_e32 v245, 0xffff0000, v241
	v_pk_add_f32 v[98:99], v[98:99], v[244:245]
	v_cvt_pk_bf16_f32 v226, v100, v101
	v_cvt_pk_bf16_f32 v227, v102, v103
	v_cvt_pk_bf16_f32 v228, v96, v97
	v_cvt_pk_bf16_f32 v229, v98, v99
	s_mov_b32 s58, 0x10000
	v_lshl_add_u64 v[246:247], v[172:173], 0, s[58:59]
	global_store_dwordx4 v[246:247], v[226:229], off offset:256
	s_waitcnt vmcnt(23)
	v_lshlrev_b32_e32 v252, 16, v16
	v_and_b32_e32 v253, 0xffff0000, v16
	v_pk_mul_f32 v[92:93], v[92:93], v[252:253]
	v_lshlrev_b32_e32 v178, 16, v17
	v_and_b32_e32 v179, 0xffff0000, v17
	v_pk_mul_f32 v[94:95], v[94:95], v[178:179]
	v_lshlrev_b32_e32 v244, 16, v18
	v_and_b32_e32 v245, 0xffff0000, v18
	v_pk_mul_f32 v[88:89], v[88:89], v[244:245]
	v_lshlrev_b32_e32 v246, 16, v19
	v_and_b32_e32 v247, 0xffff0000, v19
	v_pk_mul_f32 v[90:91], v[90:91], v[246:247]
	v_lshlrev_b32_e32 v252, 16, v32
	v_and_b32_e32 v253, 0xffff0000, v32
	v_pk_add_f32 v[92:93], v[92:93], v[252:253]
	v_lshlrev_b32_e32 v178, 16, v33
	v_and_b32_e32 v179, 0xffff0000, v33
	v_pk_add_f32 v[94:95], v[94:95], v[178:179]
	v_lshlrev_b32_e32 v244, 16, v34
	v_and_b32_e32 v245, 0xffff0000, v34
	v_pk_add_f32 v[88:89], v[88:89], v[244:245]
	v_lshlrev_b32_e32 v246, 16, v35
	v_and_b32_e32 v247, 0xffff0000, v35
	v_pk_add_f32 v[90:91], v[90:91], v[246:247]
	v_cvt_pk_bf16_f32 v16, v92, v93
	v_cvt_pk_bf16_f32 v17, v94, v95
	v_cvt_pk_bf16_f32 v18, v88, v89
	v_cvt_pk_bf16_f32 v19, v90, v91
	s_mov_b32 s58, 0x18000
	v_lshl_add_u64 v[252:253], v[172:173], 0, s[58:59]
	global_store_dwordx4 v[252:253], v[16:19], off
	s_waitcnt vmcnt(23)
	v_lshlrev_b32_e32 v178, 16, v24
	v_and_b32_e32 v179, 0xffff0000, v24
	v_pk_mul_f32 v[84:85], v[84:85], v[178:179]
	v_lshlrev_b32_e32 v244, 16, v25
	v_and_b32_e32 v245, 0xffff0000, v25
	v_pk_mul_f32 v[86:87], v[86:87], v[244:245]
	v_lshlrev_b32_e32 v246, 16, v26
	v_and_b32_e32 v247, 0xffff0000, v26
	v_pk_mul_f32 v[80:81], v[80:81], v[246:247]
	v_lshlrev_b32_e32 v252, 16, v27
	v_and_b32_e32 v253, 0xffff0000, v27
	v_pk_mul_f32 v[82:83], v[82:83], v[252:253]
	v_lshlrev_b32_e32 v178, 16, v44
	v_and_b32_e32 v179, 0xffff0000, v44
	v_pk_add_f32 v[84:85], v[84:85], v[178:179]
	v_lshlrev_b32_e32 v244, 16, v45
	v_and_b32_e32 v245, 0xffff0000, v45
	v_pk_add_f32 v[86:87], v[86:87], v[244:245]
	v_lshlrev_b32_e32 v246, 16, v46
	v_and_b32_e32 v247, 0xffff0000, v46
	v_pk_add_f32 v[80:81], v[80:81], v[246:247]
	v_lshlrev_b32_e32 v252, 16, v47
	v_and_b32_e32 v253, 0xffff0000, v47
	v_pk_add_f32 v[82:83], v[82:83], v[252:253]
	v_cvt_pk_bf16_f32 v24, v84, v85
	v_cvt_pk_bf16_f32 v25, v86, v87
	v_cvt_pk_bf16_f32 v26, v80, v81
	v_cvt_pk_bf16_f32 v27, v82, v83
	s_mov_b32 s58, 0x18000
	v_lshl_add_u64 v[178:179], v[172:173], 0, s[58:59]
	global_store_dwordx4 v[178:179], v[24:27], off offset:256
	s_waitcnt vmcnt(21)
	v_lshlrev_b32_e32 v244, 16, v136
	v_and_b32_e32 v245, 0xffff0000, v136
	v_pk_mul_f32 v[76:77], v[76:77], v[244:245]
	v_lshlrev_b32_e32 v246, 16, v137
	v_and_b32_e32 v247, 0xffff0000, v137
	v_pk_mul_f32 v[78:79], v[78:79], v[246:247]
	v_lshlrev_b32_e32 v252, 16, v138
	v_and_b32_e32 v253, 0xffff0000, v138
	v_pk_mul_f32 v[72:73], v[72:73], v[252:253]
	v_lshlrev_b32_e32 v178, 16, v139
	v_and_b32_e32 v179, 0xffff0000, v139
	v_pk_mul_f32 v[74:75], v[74:75], v[178:179]
	v_lshlrev_b32_e32 v244, 16, v152
	v_and_b32_e32 v245, 0xffff0000, v152
	v_pk_add_f32 v[76:77], v[76:77], v[244:245]
	v_lshlrev_b32_e32 v246, 16, v153
	v_and_b32_e32 v247, 0xffff0000, v153
	v_pk_add_f32 v[78:79], v[78:79], v[246:247]
	v_lshlrev_b32_e32 v252, 16, v154
	v_and_b32_e32 v253, 0xffff0000, v154
	v_pk_add_f32 v[72:73], v[72:73], v[252:253]
	v_lshlrev_b32_e32 v178, 16, v155
	v_and_b32_e32 v179, 0xffff0000, v155
	v_pk_add_f32 v[74:75], v[74:75], v[178:179]
	v_cvt_pk_bf16_f32 v136, v76, v77
	v_cvt_pk_bf16_f32 v137, v78, v79
	v_cvt_pk_bf16_f32 v138, v72, v73
	v_cvt_pk_bf16_f32 v139, v74, v75
	s_mov_b32 s58, 0x40000
	v_lshl_add_u64 v[244:245], v[172:173], 0, s[58:59]
	global_store_dwordx4 v[244:245], v[136:139], off
	s_waitcnt vmcnt(21)
	v_lshlrev_b32_e32 v246, 16, v148
	v_and_b32_e32 v247, 0xffff0000, v148
	v_pk_mul_f32 v[68:69], v[68:69], v[246:247]
	v_lshlrev_b32_e32 v252, 16, v149
	v_and_b32_e32 v253, 0xffff0000, v149
	v_pk_mul_f32 v[70:71], v[70:71], v[252:253]
	v_lshlrev_b32_e32 v178, 16, v150
	v_and_b32_e32 v179, 0xffff0000, v150
	v_pk_mul_f32 v[64:65], v[64:65], v[178:179]
	v_lshlrev_b32_e32 v244, 16, v151
	v_and_b32_e32 v245, 0xffff0000, v151
	v_pk_mul_f32 v[66:67], v[66:67], v[244:245]
	v_lshlrev_b32_e32 v246, 16, v156
	v_and_b32_e32 v247, 0xffff0000, v156
	v_pk_add_f32 v[68:69], v[68:69], v[246:247]
	v_lshlrev_b32_e32 v252, 16, v157
	v_and_b32_e32 v253, 0xffff0000, v157
	v_pk_add_f32 v[70:71], v[70:71], v[252:253]
	v_lshlrev_b32_e32 v178, 16, v158
	v_and_b32_e32 v179, 0xffff0000, v158
	v_pk_add_f32 v[64:65], v[64:65], v[178:179]
	v_lshlrev_b32_e32 v244, 16, v159
	v_and_b32_e32 v245, 0xffff0000, v159
	v_pk_add_f32 v[66:67], v[66:67], v[244:245]
	v_cvt_pk_bf16_f32 v148, v68, v69
	v_cvt_pk_bf16_f32 v149, v70, v71
	v_cvt_pk_bf16_f32 v150, v64, v65
	v_cvt_pk_bf16_f32 v151, v66, v67
	s_mov_b32 s58, 0x40000
	v_lshl_add_u64 v[246:247], v[172:173], 0, s[58:59]
	global_store_dwordx4 v[246:247], v[148:151], off offset:256
	s_waitcnt vmcnt(17)
	v_lshlrev_b32_e32 v252, 16, v140
	v_and_b32_e32 v253, 0xffff0000, v140
	v_pk_mul_f32 v[60:61], v[60:61], v[252:253]
	v_lshlrev_b32_e32 v178, 16, v141
	v_and_b32_e32 v179, 0xffff0000, v141
	v_pk_mul_f32 v[62:63], v[62:63], v[178:179]
	v_lshlrev_b32_e32 v244, 16, v142
	v_and_b32_e32 v245, 0xffff0000, v142
	v_pk_mul_f32 v[56:57], v[56:57], v[244:245]
	v_lshlrev_b32_e32 v246, 16, v143
	v_and_b32_e32 v247, 0xffff0000, v143
	v_pk_mul_f32 v[58:59], v[58:59], v[246:247]
	v_lshlrev_b32_e32 v252, 16, v180
	v_and_b32_e32 v253, 0xffff0000, v180
	v_pk_add_f32 v[60:61], v[60:61], v[252:253]
	v_lshlrev_b32_e32 v178, 16, v181
	v_and_b32_e32 v179, 0xffff0000, v181
	v_pk_add_f32 v[62:63], v[62:63], v[178:179]
	v_lshlrev_b32_e32 v244, 16, v182
	v_and_b32_e32 v245, 0xffff0000, v182
	v_pk_add_f32 v[56:57], v[56:57], v[244:245]
	v_lshlrev_b32_e32 v246, 16, v183
	v_and_b32_e32 v247, 0xffff0000, v183
	v_pk_add_f32 v[58:59], v[58:59], v[246:247]
	v_cvt_pk_bf16_f32 v140, v60, v61
	v_cvt_pk_bf16_f32 v141, v62, v63
	v_cvt_pk_bf16_f32 v142, v56, v57
	v_cvt_pk_bf16_f32 v143, v58, v59
	s_mov_b32 s58, 0x48000
	v_lshl_add_u64 v[252:253], v[172:173], 0, s[58:59]
	global_store_dwordx4 v[252:253], v[140:143], off
	s_waitcnt vmcnt(17)
	v_lshlrev_b32_e32 v178, 16, v144
	v_and_b32_e32 v179, 0xffff0000, v144
	v_pk_mul_f32 v[52:53], v[52:53], v[178:179]
	v_lshlrev_b32_e32 v244, 16, v145
	v_and_b32_e32 v245, 0xffff0000, v145
	v_pk_mul_f32 v[54:55], v[54:55], v[244:245]
	v_lshlrev_b32_e32 v246, 16, v146
	v_and_b32_e32 v247, 0xffff0000, v146
	v_pk_mul_f32 v[48:49], v[48:49], v[246:247]
	v_lshlrev_b32_e32 v252, 16, v147
	v_and_b32_e32 v253, 0xffff0000, v147
	v_pk_mul_f32 v[50:51], v[50:51], v[252:253]
	v_lshlrev_b32_e32 v178, 16, v188
	v_and_b32_e32 v179, 0xffff0000, v188
	v_pk_add_f32 v[52:53], v[52:53], v[178:179]
	v_lshlrev_b32_e32 v244, 16, v189
	v_and_b32_e32 v245, 0xffff0000, v189
	v_pk_add_f32 v[54:55], v[54:55], v[244:245]
	v_lshlrev_b32_e32 v246, 16, v190
	v_and_b32_e32 v247, 0xffff0000, v190
	v_pk_add_f32 v[48:49], v[48:49], v[246:247]
	v_lshlrev_b32_e32 v252, 16, v191
	v_and_b32_e32 v253, 0xffff0000, v191
	v_pk_add_f32 v[50:51], v[50:51], v[252:253]
	v_cvt_pk_bf16_f32 v144, v52, v53
	v_cvt_pk_bf16_f32 v145, v54, v55
	v_cvt_pk_bf16_f32 v146, v48, v49
	v_cvt_pk_bf16_f32 v147, v50, v51
	s_mov_b32 s58, 0x48000
	v_lshl_add_u64 v[178:179], v[172:173], 0, s[58:59]
	global_store_dwordx4 v[178:179], v[144:147], off offset:256
	s_waitcnt vmcnt(15)
	v_lshlrev_b32_e32 v244, 16, v128
	v_and_b32_e32 v245, 0xffff0000, v128
	v_pk_mul_f32 v[40:41], v[40:41], v[244:245]
	v_lshlrev_b32_e32 v246, 16, v129
	v_and_b32_e32 v247, 0xffff0000, v129
	v_pk_mul_f32 v[42:43], v[42:43], v[246:247]
	v_lshlrev_b32_e32 v252, 16, v130
	v_and_b32_e32 v253, 0xffff0000, v130
	v_pk_mul_f32 v[36:37], v[36:37], v[252:253]
	v_lshlrev_b32_e32 v178, 16, v131
	v_and_b32_e32 v179, 0xffff0000, v131
	v_pk_mul_f32 v[38:39], v[38:39], v[178:179]
	v_lshlrev_b32_e32 v244, 16, v184
	v_and_b32_e32 v245, 0xffff0000, v184
	v_pk_add_f32 v[40:41], v[40:41], v[244:245]
	v_lshlrev_b32_e32 v246, 16, v185
	v_and_b32_e32 v247, 0xffff0000, v185
	v_pk_add_f32 v[42:43], v[42:43], v[246:247]
	v_lshlrev_b32_e32 v252, 16, v186
	v_and_b32_e32 v253, 0xffff0000, v186
	v_pk_add_f32 v[36:37], v[36:37], v[252:253]
	v_lshlrev_b32_e32 v178, 16, v187
	v_and_b32_e32 v179, 0xffff0000, v187
	v_pk_add_f32 v[38:39], v[38:39], v[178:179]
	v_cvt_pk_bf16_f32 v128, v40, v41
	v_cvt_pk_bf16_f32 v129, v42, v43
	v_cvt_pk_bf16_f32 v130, v36, v37
	v_cvt_pk_bf16_f32 v131, v38, v39
	s_mov_b32 s58, 0x50000
	v_lshl_add_u64 v[244:245], v[172:173], 0, s[58:59]
	global_store_dwordx4 v[244:245], v[128:131], off
	s_waitcnt vmcnt(15)
	v_lshlrev_b32_e32 v246, 16, v132
	v_and_b32_e32 v247, 0xffff0000, v132
	v_pk_mul_f32 v[28:29], v[28:29], v[246:247]
	v_lshlrev_b32_e32 v252, 16, v133
	v_and_b32_e32 v253, 0xffff0000, v133
	v_pk_mul_f32 v[30:31], v[30:31], v[252:253]
	v_lshlrev_b32_e32 v178, 16, v134
	v_and_b32_e32 v179, 0xffff0000, v134
	v_pk_mul_f32 v[20:21], v[20:21], v[178:179]
	v_lshlrev_b32_e32 v244, 16, v135
	v_and_b32_e32 v245, 0xffff0000, v135
	v_pk_mul_f32 v[22:23], v[22:23], v[244:245]
	v_lshlrev_b32_e32 v246, 16, v192
	v_and_b32_e32 v247, 0xffff0000, v192
	v_pk_add_f32 v[28:29], v[28:29], v[246:247]
	v_lshlrev_b32_e32 v252, 16, v193
	v_and_b32_e32 v253, 0xffff0000, v193
	v_pk_add_f32 v[30:31], v[30:31], v[252:253]
	v_lshlrev_b32_e32 v178, 16, v194
	v_and_b32_e32 v179, 0xffff0000, v194
	v_pk_add_f32 v[20:21], v[20:21], v[178:179]
	v_lshlrev_b32_e32 v244, 16, v195
	v_and_b32_e32 v245, 0xffff0000, v195
	v_pk_add_f32 v[22:23], v[22:23], v[244:245]
	v_cvt_pk_bf16_f32 v132, v28, v29
	v_cvt_pk_bf16_f32 v133, v30, v31
	v_cvt_pk_bf16_f32 v134, v20, v21
	v_cvt_pk_bf16_f32 v135, v22, v23
	s_mov_b32 s58, 0x50000
	v_lshl_add_u64 v[246:247], v[172:173], 0, s[58:59]
	global_store_dwordx4 v[246:247], v[132:135], off offset:256
	s_waitcnt vmcnt(11)
	v_lshlrev_b32_e32 v252, 16, v120
	v_and_b32_e32 v253, 0xffff0000, v120
	v_pk_mul_f32 v[12:13], v[12:13], v[252:253]
	v_lshlrev_b32_e32 v178, 16, v121
	v_and_b32_e32 v179, 0xffff0000, v121
	v_pk_mul_f32 v[14:15], v[14:15], v[178:179]
	v_lshlrev_b32_e32 v244, 16, v122
	v_and_b32_e32 v245, 0xffff0000, v122
	v_pk_mul_f32 v[8:9], v[8:9], v[244:245]
	v_lshlrev_b32_e32 v246, 16, v123
	v_and_b32_e32 v247, 0xffff0000, v123
	v_pk_mul_f32 v[10:11], v[10:11], v[246:247]
	v_lshlrev_b32_e32 v252, 16, v196
	v_and_b32_e32 v253, 0xffff0000, v196
	v_pk_add_f32 v[12:13], v[12:13], v[252:253]
	v_lshlrev_b32_e32 v178, 16, v197
	v_and_b32_e32 v179, 0xffff0000, v197
	v_pk_add_f32 v[14:15], v[14:15], v[178:179]
	v_lshlrev_b32_e32 v244, 16, v198
	v_and_b32_e32 v245, 0xffff0000, v198
	v_pk_add_f32 v[8:9], v[8:9], v[244:245]
	v_lshlrev_b32_e32 v246, 16, v199
	v_and_b32_e32 v247, 0xffff0000, v199
	v_pk_add_f32 v[10:11], v[10:11], v[246:247]
	v_cvt_pk_bf16_f32 v120, v12, v13
	v_cvt_pk_bf16_f32 v121, v14, v15
	v_cvt_pk_bf16_f32 v122, v8, v9
	v_cvt_pk_bf16_f32 v123, v10, v11
	s_mov_b32 s58, 0x58000
	v_lshl_add_u64 v[252:253], v[172:173], 0, s[58:59]
	global_store_dwordx4 v[252:253], v[120:123], off
	s_waitcnt vmcnt(11)
	v_lshlrev_b32_e32 v178, 16, v124
	v_and_b32_e32 v179, 0xffff0000, v124
	v_pk_mul_f32 v[4:5], v[4:5], v[178:179]
	v_lshlrev_b32_e32 v244, 16, v125
	v_and_b32_e32 v245, 0xffff0000, v125
	v_pk_mul_f32 v[6:7], v[6:7], v[244:245]
	v_lshlrev_b32_e32 v246, 16, v126
	v_and_b32_e32 v247, 0xffff0000, v126
	v_pk_mul_f32 v[0:1], v[0:1], v[246:247]
	v_lshlrev_b32_e32 v252, 16, v127
	v_and_b32_e32 v253, 0xffff0000, v127
	v_pk_mul_f32 v[2:3], v[2:3], v[252:253]
	v_lshlrev_b32_e32 v178, 16, v204
	v_and_b32_e32 v179, 0xffff0000, v204
	v_pk_add_f32 v[4:5], v[4:5], v[178:179]
	v_lshlrev_b32_e32 v244, 16, v205
	v_and_b32_e32 v245, 0xffff0000, v205
	v_pk_add_f32 v[6:7], v[6:7], v[244:245]
	v_lshlrev_b32_e32 v246, 16, v206
	v_and_b32_e32 v247, 0xffff0000, v206
	v_pk_add_f32 v[0:1], v[0:1], v[246:247]
	v_lshlrev_b32_e32 v252, 16, v207
	v_and_b32_e32 v253, 0xffff0000, v207
	v_pk_add_f32 v[2:3], v[2:3], v[252:253]
	v_cvt_pk_bf16_f32 v124, v4, v5
	v_cvt_pk_bf16_f32 v125, v6, v7
	v_cvt_pk_bf16_f32 v126, v0, v1
	v_cvt_pk_bf16_f32 v127, v2, v3
	s_mov_b32 s58, 0x58000
	v_lshl_add_u64 v[178:179], v[172:173], 0, s[58:59]
	global_store_dwordx4 v[178:179], v[124:127], off offset:256
	s_branch .Lmepi_done
.Lmepi_z0:
	global_load_dwordx4 v[180:183], v[170:171], off nt
	global_load_dwordx4 v[184:187], v[170:171], off offset:256 nt
	s_mov_b32 s58, 0x20000
	v_lshl_add_u64 v[244:245], v[170:171], 0, s[58:59]
	global_load_dwordx4 v[188:191], v[244:245], off nt
	global_load_dwordx4 v[192:195], v[244:245], off offset:256 nt
	s_mov_b32 s58, 0x40000
	v_lshl_add_u64 v[246:247], v[170:171], 0, s[58:59]
	global_load_dwordx4 v[196:199], v[246:247], off nt
	global_load_dwordx4 v[200:203], v[246:247], off offset:256 nt
	s_mov_b32 s58, 0x60000
	v_lshl_add_u64 v[252:253], v[170:171], 0, s[58:59]
	global_load_dwordx4 v[204:207], v[252:253], off nt
	global_load_dwordx4 v[208:211], v[252:253], off offset:256 nt
	s_mov_b32 s58, 0x100000
	v_lshl_add_u64 v[178:179], v[170:171], 0, s[58:59]
	global_load_dwordx4 v[222:225], v[178:179], off nt
	global_load_dwordx4 v[226:229], v[178:179], off offset:256 nt
	s_mov_b32 s58, 0x120000
	v_lshl_add_u64 v[244:245], v[170:171], 0, s[58:59]
	global_load_dwordx4 v[234:237], v[244:245], off nt
	global_load_dwordx4 v[238:241], v[244:245], off offset:256 nt
	s_mov_b32 s58, 0x140000
	v_lshl_add_u64 v[246:247], v[170:171], 0, s[58:59]
	global_load_dwordx4 v[16:19], v[246:247], off nt
	global_load_dwordx4 v[24:27], v[246:247], off offset:256 nt
	s_mov_b32 s58, 0x160000
	v_lshl_add_u64 v[252:253], v[170:171], 0, s[58:59]
	global_load_dwordx4 v[32:35], v[252:253], off nt
	global_load_dwordx4 v[44:47], v[252:253], off offset:256 nt
	s_waitcnt vmcnt(15)
	v_lshlrev_b32_e32 v178, 16, v180
	v_and_b32_e32 v179, 0xffff0000, v180
	v_pk_mul_f32 v[144:145], v[144:145], v[178:179]
	v_lshlrev_b32_e32 v244, 16, v181
	v_and_b32_e32 v245, 0xffff0000, v181
	v_pk_mul_f32 v[146:147], v[146:147], v[244:245]
	v_lshlrev_b32_e32 v246, 16, v182
	v_and_b32_e32 v247, 0xffff0000, v182
	v_pk_mul_f32 v[140:141], v[140:141], v[246:247]
	v_lshlrev_b32_e32 v252, 16, v183
	v_and_b32_e32 v253, 0xffff0000, v183
	v_pk_mul_f32 v[142:143], v[142:143], v[252:253]
	v_cvt_pk_bf16_f32 v180, v144, v145
	v_cvt_pk_bf16_f32 v181, v146, v147
	v_cvt_pk_bf16_f32 v182, v140, v141
	v_cvt_pk_bf16_f32 v183, v142, v143
	global_store_dwordx4 v[172:173], v[180:183], off
	s_waitcnt vmcnt(15)
	v_lshlrev_b32_e32 v178, 16, v184
	v_and_b32_e32 v179, 0xffff0000, v184
	v_pk_mul_f32 v[132:133], v[132:133], v[178:179]
	v_lshlrev_b32_e32 v244, 16, v185
	v_and_b32_e32 v245, 0xffff0000, v185
	v_pk_mul_f32 v[134:135], v[134:135], v[244:245]
	v_lshlrev_b32_e32 v246, 16, v186
	v_and_b32_e32 v247, 0xffff0000, v186
	v_pk_mul_f32 v[128:129], v[128:129], v[246:247]
	v_lshlrev_b32_e32 v252, 16, v187
	v_and_b32_e32 v253, 0xffff0000, v187
	v_pk_mul_f32 v[130:131], v[130:131], v[252:253]
	v_cvt_pk_bf16_f32 v184, v132, v133
	v_cvt_pk_bf16_f32 v185, v134, v135
	v_cvt_pk_bf16_f32 v186, v128, v129
	v_cvt_pk_bf16_f32 v187, v130, v131
	global_store_dwordx4 v[172:173], v[184:187], off offset:256
	s_waitcnt vmcnt(15)
	v_lshlrev_b32_e32 v178, 16, v188
	v_and_b32_e32 v179, 0xffff0000, v188
	v_pk_mul_f32 v[124:125], v[124:125], v[178:179]
	v_lshlrev_b32_e32 v244, 16, v189
	v_and_b32_e32 v245, 0xffff0000, v189
	v_pk_mul_f32 v[126:127], v[126:127], v[244:245]
	v_lshlrev_b32_e32 v246, 16, v190
	v_and_b32_e32 v247, 0xffff0000, v190
	v_pk_mul_f32 v[120:121], v[120:121], v[246:247]
	v_lshlrev_b32_e32 v252, 16, v191
	v_and_b32_e32 v253, 0xffff0000, v191
	v_pk_mul_f32 v[122:123], v[122:123], v[252:253]
	v_cvt_pk_bf16_f32 v188, v124, v125
	v_cvt_pk_bf16_f32 v189, v126, v127
	v_cvt_pk_bf16_f32 v190, v120, v121
	v_cvt_pk_bf16_f32 v191, v122, v123
	s_mov_b32 s58, 0x8000
	v_lshl_add_u64 v[178:179], v[172:173], 0, s[58:59]
	global_store_dwordx4 v[178:179], v[188:191], off
	s_waitcnt vmcnt(15)
	v_lshlrev_b32_e32 v244, 16, v192
	v_and_b32_e32 v245, 0xffff0000, v192
	v_pk_mul_f32 v[116:117], v[116:117], v[244:245]
	v_lshlrev_b32_e32 v246, 16, v193
	v_and_b32_e32 v247, 0xffff0000, v193
	v_pk_mul_f32 v[118:119], v[118:119], v[246:247]
	v_lshlrev_b32_e32 v252, 16, v194
	v_and_b32_e32 v253, 0xffff0000, v194
	v_pk_mul_f32 v[112:113], v[112:113], v[252:253]
	v_lshlrev_b32_e32 v178, 16, v195
	v_and_b32_e32 v179, 0xffff0000, v195
	v_pk_mul_f32 v[114:115], v[114:115], v[178:179]
	v_cvt_pk_bf16_f32 v192, v116, v117
	v_cvt_pk_bf16_f32 v193, v118, v119
	v_cvt_pk_bf16_f32 v194, v112, v113
	v_cvt_pk_bf16_f32 v195, v114, v115
	s_mov_b32 s58, 0x8000
	v_lshl_add_u64 v[244:245], v[172:173], 0, s[58:59]
	global_store_dwordx4 v[244:245], v[192:195], off offset:256
	s_waitcnt vmcnt(15)
	v_lshlrev_b32_e32 v246, 16, v196
	v_and_b32_e32 v247, 0xffff0000, v196
	v_pk_mul_f32 v[108:109], v[108:109], v[246:247]
	v_lshlrev_b32_e32 v252, 16, v197
	v_and_b32_e32 v253, 0xffff0000, v197
	v_pk_mul_f32 v[110:111], v[110:111], v[252:253]
	v_lshlrev_b32_e32 v178, 16, v198
	v_and_b32_e32 v179, 0xffff0000, v198
	v_pk_mul_f32 v[104:105], v[104:105], v[178:179]
	v_lshlrev_b32_e32 v244, 16, v199
	v_and_b32_e32 v245, 0xffff0000, v199
	v_pk_mul_f32 v[106:107], v[106:107], v[244:245]
	v_cvt_pk_bf16_f32 v196, v108, v109
	v_cvt_pk_bf16_f32 v197, v110, v111
	v_cvt_pk_bf16_f32 v198, v104, v105
	v_cvt_pk_bf16_f32 v199, v106, v107
	s_mov_b32 s58, 0x10000
	v_lshl_add_u64 v[246:247], v[172:173], 0, s[58:59]
	global_store_dwordx4 v[246:247], v[196:199], off
	s_waitcnt vmcnt(15)
	v_lshlrev_b32_e32 v252, 16, v200
	v_and_b32_e32 v253, 0xffff0000, v200
	v_pk_mul_f32 v[100:101], v[100:101], v[252:253]
	v_lshlrev_b32_e32 v178, 16, v201
	v_and_b32_e32 v179, 0xffff0000, v201
	v_pk_mul_f32 v[102:103], v[102:103], v[178:179]
	v_lshlrev_b32_e32 v244, 16, v202
	v_and_b32_e32 v245, 0xffff0000, v202
	v_pk_mul_f32 v[96:97], v[96:97], v[244:245]
	v_lshlrev_b32_e32 v246, 16, v203
	v_and_b32_e32 v247, 0xffff0000, v203
	v_pk_mul_f32 v[98:99], v[98:99], v[246:247]
	v_cvt_pk_bf16_f32 v200, v100, v101
	v_cvt_pk_bf16_f32 v201, v102, v103
	v_cvt_pk_bf16_f32 v202, v96, v97
	v_cvt_pk_bf16_f32 v203, v98, v99
	s_mov_b32 s58, 0x10000
	v_lshl_add_u64 v[252:253], v[172:173], 0, s[58:59]
	global_store_dwordx4 v[252:253], v[200:203], off offset:256
	s_waitcnt vmcnt(15)
	v_lshlrev_b32_e32 v178, 16, v204
	v_and_b32_e32 v179, 0xffff0000, v204
	v_pk_mul_f32 v[92:93], v[92:93], v[178:179]
	v_lshlrev_b32_e32 v244, 16, v205
	v_and_b32_e32 v245, 0xffff0000, v205
	v_pk_mul_f32 v[94:95], v[94:95], v[244:245]
	v_lshlrev_b32_e32 v246, 16, v206
	v_and_b32_e32 v247, 0xffff0000, v206
	v_pk_mul_f32 v[88:89], v[88:89], v[246:247]
	v_lshlrev_b32_e32 v252, 16, v207
	v_and_b32_e32 v253, 0xffff0000, v207
	v_pk_mul_f32 v[90:91], v[90:91], v[252:253]
	v_cvt_pk_bf16_f32 v204, v92, v93
	v_cvt_pk_bf16_f32 v205, v94, v95
	v_cvt_pk_bf16_f32 v206, v88, v89
	v_cvt_pk_bf16_f32 v207, v90, v91
	s_mov_b32 s58, 0x18000
	v_lshl_add_u64 v[178:179], v[172:173], 0, s[58:59]
	global_store_dwordx4 v[178:179], v[204:207], off
	s_waitcnt vmcnt(15)
	v_lshlrev_b32_e32 v244, 16, v208
	v_and_b32_e32 v245, 0xffff0000, v208
	v_pk_mul_f32 v[84:85], v[84:85], v[244:245]
	v_lshlrev_b32_e32 v246, 16, v209
	v_and_b32_e32 v247, 0xffff0000, v209
	v_pk_mul_f32 v[86:87], v[86:87], v[246:247]
	v_lshlrev_b32_e32 v252, 16, v210
	v_and_b32_e32 v253, 0xffff0000, v210
	v_pk_mul_f32 v[80:81], v[80:81], v[252:253]
	v_lshlrev_b32_e32 v178, 16, v211
	v_and_b32_e32 v179, 0xffff0000, v211
	v_pk_mul_f32 v[82:83], v[82:83], v[178:179]
	v_cvt_pk_bf16_f32 v208, v84, v85
	v_cvt_pk_bf16_f32 v209, v86, v87
	v_cvt_pk_bf16_f32 v210, v80, v81
	v_cvt_pk_bf16_f32 v211, v82, v83
	s_mov_b32 s58, 0x18000
	v_lshl_add_u64 v[244:245], v[172:173], 0, s[58:59]
	global_store_dwordx4 v[244:245], v[208:211], off offset:256
	s_waitcnt vmcnt(15)
	v_lshlrev_b32_e32 v246, 16, v222
	v_and_b32_e32 v247, 0xffff0000, v222
	v_pk_mul_f32 v[76:77], v[76:77], v[246:247]
	v_lshlrev_b32_e32 v252, 16, v223
	v_and_b32_e32 v253, 0xffff0000, v223
	v_pk_mul_f32 v[78:79], v[78:79], v[252:253]
	v_lshlrev_b32_e32 v178, 16, v224
	v_and_b32_e32 v179, 0xffff0000, v224
	v_pk_mul_f32 v[72:73], v[72:73], v[178:179]
	v_lshlrev_b32_e32 v244, 16, v225
	v_and_b32_e32 v245, 0xffff0000, v225
	v_pk_mul_f32 v[74:75], v[74:75], v[244:245]
	v_cvt_pk_bf16_f32 v222, v76, v77
	v_cvt_pk_bf16_f32 v223, v78, v79
	v_cvt_pk_bf16_f32 v224, v72, v73
	v_cvt_pk_bf16_f32 v225, v74, v75
	s_mov_b32 s58, 0x40000
	v_lshl_add_u64 v[246:247], v[172:173], 0, s[58:59]
	global_store_dwordx4 v[246:247], v[222:225], off
	s_waitcnt vmcnt(15)
	v_lshlrev_b32_e32 v252, 16, v226
	v_and_b32_e32 v253, 0xffff0000, v226
	v_pk_mul_f32 v[68:69], v[68:69], v[252:253]
	v_lshlrev_b32_e32 v178, 16, v227
	v_and_b32_e32 v179, 0xffff0000, v227
	v_pk_mul_f32 v[70:71], v[70:71], v[178:179]
	v_lshlrev_b32_e32 v244, 16, v228
	v_and_b32_e32 v245, 0xffff0000, v228
	v_pk_mul_f32 v[64:65], v[64:65], v[244:245]
	v_lshlrev_b32_e32 v246, 16, v229
	v_and_b32_e32 v247, 0xffff0000, v229
	v_pk_mul_f32 v[66:67], v[66:67], v[246:247]
	v_cvt_pk_bf16_f32 v226, v68, v69
	v_cvt_pk_bf16_f32 v227, v70, v71
	v_cvt_pk_bf16_f32 v228, v64, v65
	v_cvt_pk_bf16_f32 v229, v66, v67
	s_mov_b32 s58, 0x40000
	v_lshl_add_u64 v[252:253], v[172:173], 0, s[58:59]
	global_store_dwordx4 v[252:253], v[226:229], off offset:256
	s_waitcnt vmcnt(15)
	v_lshlrev_b32_e32 v178, 16, v234
	v_and_b32_e32 v179, 0xffff0000, v234
	v_pk_mul_f32 v[60:61], v[60:61], v[178:179]
	v_lshlrev_b32_e32 v244, 16, v235
	v_and_b32_e32 v245, 0xffff0000, v235
	v_pk_mul_f32 v[62:63], v[62:63], v[244:245]
	v_lshlrev_b32_e32 v246, 16, v236
	v_and_b32_e32 v247, 0xffff0000, v236
	v_pk_mul_f32 v[56:57], v[56:57], v[246:247]
	v_lshlrev_b32_e32 v252, 16, v237
	v_and_b32_e32 v253, 0xffff0000, v237
	v_pk_mul_f32 v[58:59], v[58:59], v[252:253]
	v_cvt_pk_bf16_f32 v234, v60, v61
	v_cvt_pk_bf16_f32 v235, v62, v63
	v_cvt_pk_bf16_f32 v236, v56, v57
	v_cvt_pk_bf16_f32 v237, v58, v59
	s_mov_b32 s58, 0x48000
	v_lshl_add_u64 v[178:179], v[172:173], 0, s[58:59]
	global_store_dwordx4 v[178:179], v[234:237], off
	s_waitcnt vmcnt(15)
	v_lshlrev_b32_e32 v244, 16, v238
	v_and_b32_e32 v245, 0xffff0000, v238
	v_pk_mul_f32 v[52:53], v[52:53], v[244:245]
	v_lshlrev_b32_e32 v246, 16, v239
	v_and_b32_e32 v247, 0xffff0000, v239
	v_pk_mul_f32 v[54:55], v[54:55], v[246:247]
	v_lshlrev_b32_e32 v252, 16, v240
	v_and_b32_e32 v253, 0xffff0000, v240
	v_pk_mul_f32 v[48:49], v[48:49], v[252:253]
	v_lshlrev_b32_e32 v178, 16, v241
	v_and_b32_e32 v179, 0xffff0000, v241
	v_pk_mul_f32 v[50:51], v[50:51], v[178:179]
	v_cvt_pk_bf16_f32 v238, v52, v53
	v_cvt_pk_bf16_f32 v239, v54, v55
	v_cvt_pk_bf16_f32 v240, v48, v49
	v_cvt_pk_bf16_f32 v241, v50, v51
	s_mov_b32 s58, 0x48000
	v_lshl_add_u64 v[244:245], v[172:173], 0, s[58:59]
	global_store_dwordx4 v[244:245], v[238:241], off offset:256
	s_waitcnt vmcnt(15)
	v_lshlrev_b32_e32 v246, 16, v16
	v_and_b32_e32 v247, 0xffff0000, v16
	v_pk_mul_f32 v[40:41], v[40:41], v[246:247]
	v_lshlrev_b32_e32 v252, 16, v17
	v_and_b32_e32 v253, 0xffff0000, v17
	v_pk_mul_f32 v[42:43], v[42:43], v[252:253]
	v_lshlrev_b32_e32 v178, 16, v18
	v_and_b32_e32 v179, 0xffff0000, v18
	v_pk_mul_f32 v[36:37], v[36:37], v[178:179]
	v_lshlrev_b32_e32 v244, 16, v19
	v_and_b32_e32 v245, 0xffff0000, v19
	v_pk_mul_f32 v[38:39], v[38:39], v[244:245]
	v_cvt_pk_bf16_f32 v16, v40, v41
	v_cvt_pk_bf16_f32 v17, v42, v43
	v_cvt_pk_bf16_f32 v18, v36, v37
	v_cvt_pk_bf16_f32 v19, v38, v39
	s_mov_b32 s58, 0x50000
	v_lshl_add_u64 v[246:247], v[172:173], 0, s[58:59]
	global_store_dwordx4 v[246:247], v[16:19], off
	s_waitcnt vmcnt(15)
	v_lshlrev_b32_e32 v252, 16, v24
	v_and_b32_e32 v253, 0xffff0000, v24
	v_pk_mul_f32 v[28:29], v[28:29], v[252:253]
	v_lshlrev_b32_e32 v178, 16, v25
	v_and_b32_e32 v179, 0xffff0000, v25
	v_pk_mul_f32 v[30:31], v[30:31], v[178:179]
	v_lshlrev_b32_e32 v244, 16, v26
	v_and_b32_e32 v245, 0xffff0000, v26
	v_pk_mul_f32 v[20:21], v[20:21], v[244:245]
	v_lshlrev_b32_e32 v246, 16, v27
	v_and_b32_e32 v247, 0xffff0000, v27
	v_pk_mul_f32 v[22:23], v[22:23], v[246:247]
	v_cvt_pk_bf16_f32 v24, v28, v29
	v_cvt_pk_bf16_f32 v25, v30, v31
	v_cvt_pk_bf16_f32 v26, v20, v21
	v_cvt_pk_bf16_f32 v27, v22, v23
	s_mov_b32 s58, 0x50000
	v_lshl_add_u64 v[252:253], v[172:173], 0, s[58:59]
	global_store_dwordx4 v[252:253], v[24:27], off offset:256
	s_waitcnt vmcnt(15)
	v_lshlrev_b32_e32 v178, 16, v32
	v_and_b32_e32 v179, 0xffff0000, v32
	v_pk_mul_f32 v[12:13], v[12:13], v[178:179]
	v_lshlrev_b32_e32 v244, 16, v33
	v_and_b32_e32 v245, 0xffff0000, v33
	v_pk_mul_f32 v[14:15], v[14:15], v[244:245]
	v_lshlrev_b32_e32 v246, 16, v34
	v_and_b32_e32 v247, 0xffff0000, v34
	v_pk_mul_f32 v[8:9], v[8:9], v[246:247]
	v_lshlrev_b32_e32 v252, 16, v35
	v_and_b32_e32 v253, 0xffff0000, v35
	v_pk_mul_f32 v[10:11], v[10:11], v[252:253]
	v_cvt_pk_bf16_f32 v32, v12, v13
	v_cvt_pk_bf16_f32 v33, v14, v15
	v_cvt_pk_bf16_f32 v34, v8, v9
	v_cvt_pk_bf16_f32 v35, v10, v11
	s_mov_b32 s58, 0x58000
	v_lshl_add_u64 v[178:179], v[172:173], 0, s[58:59]
	global_store_dwordx4 v[178:179], v[32:35], off
	s_waitcnt vmcnt(15)
	v_lshlrev_b32_e32 v244, 16, v44
	v_and_b32_e32 v245, 0xffff0000, v44
	v_pk_mul_f32 v[4:5], v[4:5], v[244:245]
	v_lshlrev_b32_e32 v246, 16, v45
	v_and_b32_e32 v247, 0xffff0000, v45
	v_pk_mul_f32 v[6:7], v[6:7], v[246:247]
	v_lshlrev_b32_e32 v252, 16, v46
	v_and_b32_e32 v253, 0xffff0000, v46
	v_pk_mul_f32 v[0:1], v[0:1], v[252:253]
	v_lshlrev_b32_e32 v178, 16, v47
	v_and_b32_e32 v179, 0xffff0000, v47
	v_pk_mul_f32 v[2:3], v[2:3], v[178:179]
	v_cvt_pk_bf16_f32 v44, v4, v5
	v_cvt_pk_bf16_f32 v45, v6, v7
	v_cvt_pk_bf16_f32 v46, v0, v1
	v_cvt_pk_bf16_f32 v47, v2, v3
	s_mov_b32 s58, 0x58000
	v_lshl_add_u64 v[244:245], v[172:173], 0, s[58:59]
	global_store_dwordx4 v[244:245], v[44:47], off offset:256
.Lmepi_done:
	s_andn2_b64 vcc, exec, s[2:3]
	s_mov_b64 s[2:3], -1
	s_cbranch_vccnz .LBB0_1011
	s_andn2_b64 vcc, exec, s[6:7]
	s_cbranch_vccnz .LBB0_1010
	s_barrier
	s_branch .LBB0_1010
